# differential attention: per-lane softmax row sums via 8 v_mfma_f32_4x4x4_16b_bf16 (ones A operand) per tile instead of 16 v_dot2c: VALU relief in a VALU-bound loop
# baseline (speedup 1.0000x reference)
; #define LAS __attribute__((address_space(3)))
; #define AD_GLOAD_K(t) do { const char* kt_ = (const char*)Kb + (size_t)AD_TILE(t) * 64 * kpitch * 2; \
;     _Pragma("unroll") for (int i_ = 0; i_ < KPT; ++i_) { if (MODE == 1) asm volatile("" : "+v"(kgo[i_])); if (i_ + 1 < KPT || kact1) kreg[i_] = *(const u32x4*)(kt_ + kgo[i_]); } } while (0)
; #define AD_GLOAD_V(t) do { const char* vt_ = (const char*)Vb + (size_t)AD_TILE(t) * 64 * vpitch * 2; \
;     _Pragma("unroll") for (int i_ = 0; i_ < VPT; ++i_) { if (MODE == 1) asm volatile("" : "+v"(vgo[i_])); vreg[i_] = *(const u32x4*)(vt_ + vgo[i_]); } } while (0)
; template <int KW, int DQK, int DV, int MODE> ...
;     ...
;     bf16x8 qf[DQK / 16];
; #pragma unroll
;     for (int d0 = 0; d0 < DQK / 16; ++d0) qf[d0] = *(const bf16x8*)(Qw + (size_t)r32 * qpitch + d0 * 16 + hi * 8);
;     u32x4 kreg[KPT], vreg[VPT];
;     unsigned kgo[KPT], klo[KPT], vgo[VPT], vlo[VPT];
; #pragma unroll
;     for (int i_ = 0; i_ < KPT; ++i_) { const int c_ = tid + i_ * 512; const int key_ = c_ / KCH, part_ = c_ % KCH; kgo[i_] = (unsigned)(key_ * kpitch + part_ * 8) * 2u; klo[i_] = (unsigned)(key_ * KP + part_ * 16); }
; #pragma unroll
;     for (int i_ = 0; i_ < VPT; ++i_) { const int c_ = tid + i_ * 512; const int key_ = c_ / VCH, part_ = c_ % VCH; vgo[i_] = (unsigned)(key_ * vpitch + part_ * 8) * 2u; vlo[i_] = (unsigned)(2 * KT + key_ * VP + part_ * 16); }
;     const bool kact1 = (NKC % 512 == 0) || (tid + (KPT - 1) * 512 < NKC);
;     ...
;     float l = 0.f;
; #pragma unroll
;     for (int d0 = 0; d0 < DV / 32; ++d0)
; #pragma unroll
;         for (int r = 0; r < 16; ++r) o[d0][r] = 0.f;
;     constexpr int NT = S / 64;
;     const int koff = r32 * KP + (kco + hi * 8) * 2;
;     const int voff = 2 * KT + (4 * hi + ((lane & 15) >> 2)) * VP + (((lane >> 4) & 1) * 16 + (lane & 3) * 4) * 2;
;     { u32x4 kreg0[KPT];
;       { const char* kt_ = (const char*)Kb + (size_t)AD_TILE(0) * 64 * kpitch * 2;
;         _Pragma("unroll") for (int i_ = 0; i_ < KPT; ++i_) { if (i_ + 1 < KPT || kact1) kreg0[i_] = *(const u32x4*)(kt_ + kgo[i_]); } }
;       AD_GLOAD_K(1); AD_GLOAD_V(0);
;       _Pragma("unroll") for (int i_ = 0; i_ < KPT; ++i_) { if (i_ + 1 < KPT || kact1) *(LAS u32x4*)(lds + klo[i_]) = kreg0[i_]; } }
;     __syncthreads();
;     u32x4 pw[4];
;     { f32x16 pc0, pc1;
;       AD_CINIT(pc0, pc1, 0);
.LBB0_459:
	s_or_b64 exec, exec, s[48:49]
	s_lshl_b32 s29, s78, 7
	s_and_b32 s29, s29, 0x1f80
	s_or_b32 s56, s29, s14
	s_ashr_i32 s51, s50, 31
	s_lshl_b64 s[48:49], s[50:51], 21
	s_lshl_b32 s29, s56, 8
	s_add_u32 s36, s79, s48
	s_addc_u32 s37, s80, s49
	s_add_u32 s29, s36, s29
	s_addc_u32 s36, s37, 0
	s_add_u32 s52, s29, s66
	s_addc_u32 s53, s36, s67
	s_add_u32 s48, s81, s48
	s_addc_u32 s49, s82, s49
	s_lshl_b32 s50, s50, 7
	s_ashr_i32 s51, s50, 31
	s_lshl_b64 s[50:51], s[50:51], 1
	s_add_u32 s50, s83, s50
	v_lshl_add_u64 v[16:17], s[52:53], 0, v[128:129]
	v_mov_b32_e32 v201, v129
	s_addc_u32 s51, s84, s51
	v_lshl_add_u64 v[16:17], v[16:17], 0, v[200:201]
	s_waitcnt lgkmcnt(0)
	s_barrier
	global_load_dwordx4 v[130:133], v[16:17], off
	global_load_dwordx4 v[134:137], v[16:17], off offset:32
	global_load_dwordx4 v[138:141], v[16:17], off offset:64
	global_load_dwordx4 v[142:145], v[16:17], off offset:96
	s_add_u32 s52, s48, 0x4000
	v_lshl_add_u64 v[16:17], s[48:49], 0, v[180:181]
	v_lshl_add_u64 v[20:21], s[48:49], 0, v[184:185]
	s_addc_u32 s53, s49, 0
	v_mov_b32_e32 v201, v180
	v_mov_b32_e32 v208, v184
	v_mov_b32_e32 v209, v192
	v_mov_b32_e32 v219, v194
	global_load_dwordx4 v[16:19], v[16:17], off
	s_cmpk_gt_u32 s56, 0x26d
	global_load_dwordx4 v[20:23], v[20:21], off
	global_load_dwordx4 v[48:51], v201, s[52:53]
	global_load_dwordx4 v[52:55], v208, s[52:53]
	global_load_dwordx4 v[56:59], v209, s[50:51]
	global_load_dwordx4 v[60:63], v219, s[50:51]
	v_add_u32_e32 v64, 0, v182
	v_add_u32_e32 v65, 0, v190
	s_cselect_b64 s[52:53], -1, 0
	s_cmpk_lt_u32 s56, 0x26e
	s_mov_b64 s[54:55], -1
	s_waitcnt vmcnt(5)
	ds_write_b128 v64, v[16:19]
	s_waitcnt vmcnt(4)
	ds_write_b128 v65, v[20:23]
	s_waitcnt lgkmcnt(0)
	s_barrier
	s_cbranch_scc0 .LBB0_461
	v_or_b32_e32 v16, s56, v191
	v_sub_u32_e32 v16, v193, v16
	v_lshl_add_u32 v28, v16, 2, s90
	v_add_u32_e32 v16, 0xffc, v28
	v_add_u32_e32 v17, 0x107c, v28
	v_add_u32_e32 v18, 0x1004, v28
	v_add_u32_e32 v19, 0x1084, v28
	v_add_u32_e32 v20, 0x101c, v28
	v_add_u32_e32 v21, 0x109c, v28
	v_add_u32_e32 v22, 0x1024, v28
	v_add_u32_e32 v23, 0x10a4, v28
	v_add_u32_e32 v24, 0x103c, v28
	v_add_u32_e32 v25, 0x10bc, v28
	v_add_u32_e32 v26, 0x1044, v28
	v_add_u32_e32 v27, 0x10c4, v28
	v_add_u32_e32 v29, 0x105c, v28
	v_add_u32_e32 v30, 0x10dc, v28
	v_add_u32_e32 v31, 0x1064, v28
	ds_read2_b32 v[32:33], v16 offset1:1
	ds_read2_b32 v[16:17], v17 offset1:1
	ds_read2_b32 v[34:35], v18 offset1:1
	ds_read2_b32 v[18:19], v19 offset1:1
	ds_read2_b32 v[36:37], v20 offset1:1
	ds_read2_b32 v[20:21], v21 offset1:1
	ds_read2_b32 v[38:39], v22 offset1:1
	ds_read2_b32 v[22:23], v23 offset1:1
	ds_read2_b32 v[40:41], v24 offset1:1
	ds_read2_b32 v[24:25], v25 offset1:1
	ds_read2_b32 v[42:43], v26 offset1:1
	ds_read2_b32 v[26:27], v27 offset1:1
	v_add_u32_e32 v66, 0x10e4, v28
	ds_read2_b32 v[44:45], v29 offset1:1
	ds_read2_b32 v[28:29], v30 offset1:1
	ds_read2_b32 v[46:47], v31 offset1:1
	ds_read2_b32 v[30:31], v66 offset1:1
	s_mov_b64 s[54:55], 0

; #define AD_LSTORE_K(b) do { \
;     _Pragma("unroll") for (int i_ = 0; i_ < KPT; ++i_) { if (i_ + 1 < KPT || kact1) *(LAS u32x4*)(lds + (b) * KT + klo[i_]) = kreg[i_]; } } while (0)
; #define AD_LSTORE_V(b) do { \
;     _Pragma("unroll") for (int i_ = 0; i_ < VPT; ++i_) *(LAS u32x4*)(lds + (b) * VT + vlo[i_]) = vreg[i_]; } while (0)
; template <int KW, int DQK, int DV, int MODE> ...
;     ...
;     { f32x16 pc0, pc1;
;       AD_CINIT(pc0, pc1, 0);
;       qk_tile<DQK, KP>(pc0, pc1, lds + koff, qf);
;       exp_tile(pc0, pc1);
;       pack_tile(pc0, pc1, pw); }
;     AD_LSTORE_K(1); AD_LSTORE_V(0);
;     __syncthreads();
;     float ls[4] = {0.f, 0.f, 0.f, 0.f};
;     f32x16 osum;
; #pragma unroll
;     for (int r = 0; r < 16; ++r) osum[r] = 0.f;
;     bf16x8 onesf;
; #pragma unroll
;     for (int j = 0; j < 8; ++j) onesf[j] = (r32 == 0) ? (short)0x3f80 : (short)0;
;     f32x16 cvec;
; #pragma unroll
;     for (int r = 0; r < 16; ++r) cvec[r] = nbound;
;     asm volatile("" : "+v"(cvec));
;     ...
;     if (MODE == 1) {
;         int t1 = (qtok0 - 622 >= 0) ? (qtok0 - 622) / 64 + 1 : 0; t1 = t1 < 1 ? 1 : (t1 > NT ? NT : t1);
;         int t2 = (qtok0 + 590 + 63) / 64; t2 = t2 < t1 ? t1 : (t2 > NT ? NT : t2);
;         int t = 1;
;         { const float c_ = dtab[0];
; #pragma unroll
;           for (int r = 0; r < 16; ++r) cvec[r] = c_;
;           asm volatile("" : "+v"(cvec)); }
.LBB0_463:
	ds_read_b128 v[66:69], v195 offset:8704
	ds_read_b128 v[70:73], v195
	ds_read_b128 v[74:77], v195 offset:32
	s_add_i32 s29, s56, 0xfffffd92
	s_lshr_b32 s54, s29, 6
	s_waitcnt lgkmcnt(2)
	v_mfma_f32_32x32x16_bf16 v[16:31], v[66:69], v[130:133], v[16:31]
	ds_read_b128 v[66:69], v195 offset:8736
	s_add_i32 s54, s54, 1
	s_and_b64 s[52:53], s[52:53], exec
	s_cselect_b32 s52, s54, 1
	s_mov_b32 s57, 1
	s_cmp_lt_u32 s52, 2
	s_waitcnt lgkmcnt(2)
	v_mfma_f32_32x32x16_bf16 v[32:47], v[70:73], v[130:133], v[32:47]
	s_waitcnt lgkmcnt(0)
	v_mfma_f32_32x32x16_bf16 v[16:31], v[66:69], v[134:137], v[16:31]
	ds_read_b128 v[66:69], v195 offset:64
	ds_read_b128 v[70:73], v195 offset:8768
	v_mfma_f32_32x32x16_bf16 v[32:47], v[74:77], v[134:137], v[32:47]
	s_waitcnt lgkmcnt(0)
	v_mfma_f32_32x32x16_bf16 v[16:31], v[70:73], v[138:141], v[16:31]
	v_mfma_f32_32x32x16_bf16 v[32:47], v[66:69], v[138:141], v[32:47]
	ds_read_b128 v[66:69], v195 offset:96
	ds_read_b128 v[70:73], v195 offset:8800
	s_waitcnt vmcnt(3)
	ds_write_b128 v64, v[48:51] offset:17408
	s_waitcnt vmcnt(2)
	ds_write_b128 v65, v[52:55] offset:17408
	s_waitcnt vmcnt(1)
	ds_write_b128 v199, v[56:59] offset:34816
	s_waitcnt vmcnt(0)
	ds_write_b128 v207, v[60:63] offset:34816
	s_waitcnt lgkmcnt(0)
	s_barrier
	v_mfma_f32_32x32x16_bf16 v[16:31], v[70:73], v[142:145], v[16:31]
	v_mfma_f32_32x32x16_bf16 v[32:47], v[66:69], v[142:145], v[32:47]
	s_nop 10
	v_exp_f32_e32 v16, v16
	v_exp_f32_e32 v17, v17
	v_exp_f32_e32 v18, v18
	v_exp_f32_e32 v19, v19
	v_exp_f32_e32 v20, v20
	v_exp_f32_e32 v21, v21
	v_exp_f32_e32 v22, v22
	v_exp_f32_e32 v23, v23
	v_exp_f32_e32 v24, v24
	v_exp_f32_e32 v25, v25
	v_exp_f32_e32 v26, v26
	v_exp_f32_e32 v27, v27
	v_exp_f32_e32 v28, v28
	v_exp_f32_e32 v29, v29
	v_exp_f32_e32 v30, v30
	v_exp_f32_e32 v31, v31
	v_cvt_pk_bf16_f32 v150, v16, v17
	v_cvt_pk_bf16_f32 v151, v18, v19
	v_cvt_pk_bf16_f32 v152, v20, v21
	v_cvt_pk_bf16_f32 v153, v22, v23
	v_cvt_pk_bf16_f32 v146, v24, v25
	v_cvt_pk_bf16_f32 v147, v26, v27
	v_cvt_pk_bf16_f32 v148, v28, v29
	v_cvt_pk_bf16_f32 v149, v30, v31
	v_mov_b64_e32 v[30:31], v[14:15]
	v_mov_b64_e32 v[28:29], v[12:13]
	v_mov_b64_e32 v[26:27], v[10:11]
	v_mov_b64_e32 v[24:25], v[8:9]
	v_mov_b64_e32 v[22:23], v[6:7]
	v_mov_b64_e32 v[20:21], v[4:5]
	v_mov_b64_e32 v[18:19], v[2:3]
	v_mov_b64_e32 v[16:17], v[0:1]
	v_exp_f32_e32 v32, v32
	v_mov_b32_e32 v16, s90
	ds_read_b32 v80, v16
	v_exp_f32_e32 v33, v33
	v_exp_f32_e32 v34, v34
	v_exp_f32_e32 v35, v35
	v_exp_f32_e32 v36, v36
	v_exp_f32_e32 v37, v37
	v_exp_f32_e32 v38, v38
	v_exp_f32_e32 v39, v39
	v_exp_f32_e32 v40, v40
	v_exp_f32_e32 v41, v41
	v_exp_f32_e32 v42, v42
	v_exp_f32_e32 v43, v43
	v_exp_f32_e32 v44, v44
	v_exp_f32_e32 v45, v45
	v_exp_f32_e32 v46, v46
	v_exp_f32_e32 v47, v47
	v_cvt_pk_bf16_f32 v158, v32, v33
	v_cvt_pk_bf16_f32 v159, v34, v35
	v_cvt_pk_bf16_f32 v160, v36, v37
	v_cvt_pk_bf16_f32 v161, v38, v39
	v_cvt_pk_bf16_f32 v154, v40, v41
	v_cvt_pk_bf16_f32 v155, v42, v43
	v_cvt_pk_bf16_f32 v156, v44, v45
	v_cvt_pk_bf16_f32 v157, v46, v47
	s_waitcnt lgkmcnt(0)
	v_mov_b32_e32 v81, v80
	v_mov_b32_e32 v82, v80
	v_mov_b32_e32 v83, v80
	v_mov_b32_e32 v84, v80
	v_mov_b32_e32 v85, v80
	v_mov_b32_e32 v86, v80
	v_mov_b32_e32 v87, v80
	v_mov_b32_e32 v88, v80
	v_mov_b32_e32 v89, v80
	v_mov_b32_e32 v90, v80
	v_mov_b32_e32 v91, v80
	v_mov_b32_e32 v92, v80
	v_mov_b32_e32 v93, v80
	v_mov_b32_e32 v94, v80
	v_mov_b32_e32 v95, v80
	s_cbranch_scc1 .LBB0_467
	v_mov_b32_e32 v16, 0
	s_mov_b32 s58, 1
	s_mov_b32 s53, 64
	s_mov_b32 s55, 0x8000
	v_mov_b32_e32 v17, v16
	v_mov_b32_e32 v18, v16
	v_mov_b32_e32 v19, v16
	v_mov_b32_e32 v20, v16
	v_mov_b32_e32 v21, v16
	v_mov_b32_e32 v22, v16
	v_mov_b32_e32 v23, v16
	v_mov_b32_e32 v24, v16
	v_mov_b32_e32 v25, v16
	v_mov_b32_e32 v26, v16
	v_mov_b32_e32 v27, v16
	v_mov_b32_e32 v28, v16
	v_mov_b32_e32 v29, v16
	v_mov_b32_e32 v30, v16
	v_mov_b32_e32 v31, v16
	v_mov_b32_e32 v32, v16
	v_mov_b32_e32 v33, v16
	v_mov_b32_e32 v34, v16
	v_mov_b32_e32 v35, v16
	v_mov_b32_e32 v36, v16
	v_mov_b32_e32 v37, v16
	v_mov_b32_e32 v38, v16
	v_mov_b32_e32 v39, v16
	v_mov_b32_e32 v40, v16
	v_mov_b32_e32 v41, v16
	v_mov_b32_e32 v42, v16
	v_mov_b32_e32 v43, v16
	v_mov_b32_e32 v44, v16
	v_mov_b32_e32 v45, v16
	v_mov_b32_e32 v46, v16
	v_mov_b32_e32 v47, v16
	v_mov_b32_e32 v48, v16
	v_mov_b32_e32 v49, v16
	v_mov_b32_e32 v50, v16
	v_mov_b32_e32 v51, v16
	v_mov_b32_e32 v52, v16
	v_mov_b32_e32 v53, v16
	v_mov_b32_e32 v54, v16
	v_mov_b32_e32 v55, v16
	v_mov_b32_e32 v56, v16
	v_mov_b32_e32 v57, v16
	v_mov_b32_e32 v58, v16
	v_mov_b32_e32 v59, v16
	v_mov_b32_e32 v60, v16
	v_mov_b32_e32 v61, v16
	v_mov_b32_e32 v62, v16
	v_mov_b32_e32 v63, v16
	v_mov_b32_e32 v64, v16
	v_mov_b32_e32 v65, v16
	v_mov_b32_e32 v66, v16
	v_mov_b32_e32 v67, v16
	v_mov_b32_e32 v68, v16
	v_mov_b32_e32 v69, v16
	v_mov_b32_e32 v70, v16
	v_mov_b32_e32 v71, v16
	v_mov_b32_e32 v72, v16
	v_mov_b32_e32 v73, v16
	v_mov_b32_e32 v74, v16
	v_mov_b32_e32 v75, v16
	v_mov_b32_e32 v76, v16
	v_mov_b32_e32 v77, v16
	v_mov_b32_e32 v78, v16
	v_mov_b32_e32 v79, v16
	v_mov_b32_e32 v220, v16
	v_mov_b32_e32 v221, v16
	v_mov_b32_e32 v222, v16
	v_mov_b32_e32 v223, v16
	v_mov_b32_e32 v210, 0x3f803f80
	v_mov_b32_e32 v211, 0x3f803f80
.LBB0_465:
	s_add_i32 s57, s58, 1
	s_and_b32 s29, s55, 0x1fc000
	s_add_u32 s60, s48, s29
	s_addc_u32 s61, s49, 0
	s_and_b32 s29, s53, 0x1fc0
	s_mul_i32 s29, s29, 0x8c00
	global_load_dwordx4 v[162:165], v201, s[60:61]
	global_load_dwordx4 v[166:169], v208, s[60:61]
	s_add_u32 s60, s50, s29
	s_addc_u32 s61, s51, 0
	global_load_dwordx4 v[170:173], v209, s[60:61]
	global_load_dwordx4 v[174:177], v219, s[60:61]
	s_and_b32 s58, s58, 1
	s_mul_i32 s29, s58, 0x4400
	v_add_u32_e32 v186, s29, v195
	ds_read_b128 v[96:99], v186
	ds_read_b128 v[224:227], v186 offset:32
	ds_read_b128 v[228:231], v186 offset:8704
	ds_read_b128 v[232:235], v186 offset:8736
	s_xor_b32 s29, s58, 1
	s_mulk_i32 s29, 0x5000
	v_add_u32_e32 v187, s29, v202
	ds_read_b128 v[236:239], v186 offset:64
	ds_read_b64_tr_b16 v[240:241], v187 offset:34816
	ds_read_b64_tr_b16 v[242:243], v187 offset:37376
	v_mfma_f32_4x4x4_16b_bf16 v[220:223], v[210:211], v[158:159], v[220:223]
	s_waitcnt lgkmcnt(6)
	v_mfma_f32_32x32x16_bf16 v[112:127], v[96:99], v[130:133], v[80:95]
	s_waitcnt lgkmcnt(4)
	v_mfma_f32_32x32x16_bf16 v[96:111], v[228:231], v[130:133], v[80:95]
	ds_read_b128 v[228:231], v186 offset:8768
	ds_read_b64_tr_b16 v[244:245], v187 offset:34880
	ds_read_b64_tr_b16 v[246:247], v187 offset:37440
	v_mfma_f32_4x4x4_16b_bf16 v[220:223], v[210:211], v[160:161], v[220:223]
	v_mfma_f32_32x32x16_bf16 v[112:127], v[224:227], v[134:137], v[112:127]
	ds_read_b128 v[224:227], v186 offset:96
	ds_read_b64_tr_b16 v[248:249], v187 offset:34944
	ds_read_b64_tr_b16 v[250:251], v187 offset:37504
	v_mfma_f32_4x4x4_16b_bf16 v[220:223], v[210:211], v[154:155], v[220:223]
	s_waitcnt lgkmcnt(9)
	v_mfma_f32_32x32x16_bf16 v[96:111], v[232:235], v[134:137], v[96:111]
	ds_read_b128 v[232:235], v186 offset:8800
	ds_read_b64_tr_b16 v[214:215], v187 offset:35008
	ds_read_b64_tr_b16 v[216:217], v187 offset:37568
	v_mfma_f32_4x4x4_16b_bf16 v[220:223], v[210:211], v[156:157], v[220:223]
	s_nop 1
	v_mfma_f32_4x4x4_16b_bf16 v[220:223], v[210:211], v[150:151], v[220:223]
	s_waitcnt lgkmcnt(11)
	v_mfma_f32_32x32x16_bf16 v[112:127], v[236:239], v[138:141], v[112:127]
	v_mfma_f32_4x4x4_16b_bf16 v[220:223], v[210:211], v[152:153], v[220:223]
	s_waitcnt lgkmcnt(8)
	v_mfma_f32_32x32x16_bf16 v[96:111], v[228:231], v[138:141], v[96:111]
	v_mfma_f32_4x4x4_16b_bf16 v[220:223], v[210:211], v[146:147], v[220:223]
	s_waitcnt lgkmcnt(5)
	v_mfma_f32_32x32x16_bf16 v[112:127], v[224:227], v[142:145], v[112:127]
	v_mfma_f32_4x4x4_16b_bf16 v[220:223], v[210:211], v[148:149], v[220:223]
	s_waitcnt lgkmcnt(2)
	v_mfma_f32_32x32x16_bf16 v[96:111], v[232:235], v[142:145], v[96:111]
	v_mfma_f32_32x32x16_bf16 v[64:79], v[240:243], v[158:161], v[64:79]
	ds_read_b64_tr_b16 v[224:225], v187 offset:39936
	ds_read_b64_tr_b16 v[226:227], v187 offset:42496
	s_nop 4
	v_exp_f32_e32 v186, v112
	v_exp_f32_e32 v188, v113
	v_mfma_f32_32x32x16_bf16 v[48:63], v[244:247], v[158:161], v[48:63]
	ds_read_b64_tr_b16 v[228:229], v187 offset:40000
	ds_read_b64_tr_b16 v[230:231], v187 offset:42560
	v_exp_f32_e32 v189, v114
	v_exp_f32_e32 v212, v115
	v_mfma_f32_32x32x16_bf16 v[32:47], v[248:251], v[158:161], v[32:47]
	ds_read_b64_tr_b16 v[112:113], v187 offset:40064
	ds_read_b64_tr_b16 v[114:115], v187 offset:42624
	v_exp_f32_e32 v213, v116
	v_exp_f32_e32 v232, v117
	s_waitcnt lgkmcnt(6)
	v_mfma_f32_32x32x16_bf16 v[16:31], v[214:217], v[158:161], v[16:31]
	ds_read_b64_tr_b16 v[158:159], v187 offset:40128
	ds_read_b64_tr_b16 v[160:161], v187 offset:42688
	v_exp_f32_e32 v233, v118
	v_exp_f32_e32 v234, v119
	s_waitcnt lgkmcnt(6)
	v_mfma_f32_32x32x16_bf16 v[64:79], v[224:227], v[154:157], v[64:79]
	ds_read_b64_tr_b16 v[116:117], v187 offset:45056
	ds_read_b64_tr_b16 v[118:119], v187 offset:47616
	v_exp_f32_e32 v224, v120
	v_exp_f32_e32 v225, v121
	s_waitcnt lgkmcnt(6)
	v_mfma_f32_32x32x16_bf16 v[48:63], v[228:231], v[154:157], v[48:63]
	ds_read_b64_tr_b16 v[214:215], v187 offset:45120
	ds_read_b64_tr_b16 v[216:217], v187 offset:47680
	v_exp_f32_e32 v226, v122
	v_exp_f32_e32 v227, v123
	s_waitcnt lgkmcnt(6)
	v_mfma_f32_32x32x16_bf16 v[32:47], v[112:115], v[154:157], v[32:47]
	ds_read_b64_tr_b16 v[112:113], v187 offset:45184
	ds_read_b64_tr_b16 v[114:115], v187 offset:47744
	v_exp_f32_e32 v228, v124
	v_exp_f32_e32 v229, v125
	s_waitcnt lgkmcnt(6)
	v_mfma_f32_32x32x16_bf16 v[16:31], v[158:161], v[154:157], v[16:31]
	ds_read_b64_tr_b16 v[120:121], v187 offset:45248
	ds_read_b64_tr_b16 v[122:123], v187 offset:47808
	v_exp_f32_e32 v154, v126
	v_exp_f32_e32 v155, v127
	s_waitcnt lgkmcnt(6)
	v_mfma_f32_32x32x16_bf16 v[64:79], v[116:119], v[150:153], v[64:79]
	ds_read_b64_tr_b16 v[116:117], v187 offset:50176
	ds_read_b64_tr_b16 v[118:119], v187 offset:52736
	v_exp_f32_e32 v156, v96
	v_exp_f32_e32 v157, v97
	s_waitcnt lgkmcnt(6)
	v_mfma_f32_32x32x16_bf16 v[48:63], v[214:217], v[150:153], v[48:63]
	ds_read_b64_tr_b16 v[124:125], v187 offset:50240
	ds_read_b64_tr_b16 v[126:127], v187 offset:52800
	v_exp_f32_e32 v158, v98
	v_exp_f32_e32 v159, v99
	s_waitcnt lgkmcnt(6)
	v_mfma_f32_32x32x16_bf16 v[32:47], v[112:115], v[150:153], v[32:47]
	ds_read_b64_tr_b16 v[96:97], v187 offset:50304
	ds_read_b64_tr_b16 v[98:99], v187 offset:52864
	v_exp_f32_e32 v100, v100
	v_exp_f32_e32 v101, v101
	s_waitcnt lgkmcnt(6)
	v_mfma_f32_32x32x16_bf16 v[16:31], v[120:123], v[150:153], v[16:31]
	ds_read_b64_tr_b16 v[112:113], v187 offset:50368
	ds_read_b64_tr_b16 v[114:115], v187 offset:52928
	s_bitcmp1_b32 s57, 0
	s_cselect_b32 s29, 0x4400, 0
	s_add_i32 s29, s29, 0
	v_add_u32_e32 v187, s29, v182
	s_mulk_i32 s58, 0x5000
	s_waitcnt vmcnt(3)
	ds_write_b128 v187, v[162:165]
	v_add_u32_e32 v187, s29, v190
	s_add_i32 s29, s58, 0
	s_waitcnt vmcnt(2)
	ds_write_b128 v187, v[166:169]
	v_add_u32_e32 v187, s29, v196
	s_waitcnt vmcnt(1)
	ds_write_b128 v187, v[170:173] offset:34816
	v_add_u32_e32 v187, s29, v198
	s_waitcnt vmcnt(0)
	ds_write_b128 v187, v[174:177] offset:34816
	v_exp_f32_e32 v102, v102
	v_exp_f32_e32 v103, v103
	s_waitcnt lgkmcnt(10)
	v_mfma_f32_32x32x16_bf16 v[64:79], v[116:119], v[146:149], v[64:79]
	v_exp_f32_e32 v104, v104
	v_exp_f32_e32 v105, v105
	s_waitcnt lgkmcnt(8)
	v_mfma_f32_32x32x16_bf16 v[48:63], v[124:127], v[146:149], v[48:63]
	v_exp_f32_e32 v106, v106
	v_exp_f32_e32 v107, v107
	s_waitcnt lgkmcnt(6)
	v_mfma_f32_32x32x16_bf16 v[32:47], v[96:99], v[146:149], v[32:47]
	v_exp_f32_e32 v96, v108
	v_exp_f32_e32 v97, v109
	s_waitcnt lgkmcnt(4)
	v_mfma_f32_32x32x16_bf16 v[16:31], v[112:115], v[146:149], v[16:31]
	v_cvt_pk_bf16_f32 v148, v96, v97
	v_cvt_pk_bf16_f32 v147, v106, v107
	v_cvt_pk_bf16_f32 v146, v104, v105
	v_cvt_pk_bf16_f32 v153, v102, v103
	v_cvt_pk_bf16_f32 v152, v100, v101
	v_cvt_pk_bf16_f32 v151, v158, v159
	v_cvt_pk_bf16_f32 v150, v156, v157
	v_cvt_pk_bf16_f32 v157, v154, v155
	v_cvt_pk_bf16_f32 v156, v228, v229
	v_cvt_pk_bf16_f32 v155, v226, v227
	v_cvt_pk_bf16_f32 v154, v224, v225
	v_cvt_pk_bf16_f32 v161, v233, v234
	v_cvt_pk_bf16_f32 v160, v213, v232
	v_cvt_pk_bf16_f32 v159, v189, v212
	v_cvt_pk_bf16_f32 v158, v186, v188
	v_exp_f32_e32 v98, v110
	v_exp_f32_e32 v99, v111
	s_add_i32 s53, s53, 64
	s_addk_i32 s55, 0x4000
	v_cvt_pk_bf16_f32 v149, v98, v99
	s_cmp_eq_u32 s52, s57
	s_mov_b32 s58, s57
	s_waitcnt lgkmcnt(0)
	s_barrier
	s_cbranch_scc0 .LBB0_465
	s_mov_b32 s57, s54
	s_branch .LBB0_468
.LBB0_467:
	v_mov_b32_e32 v64, v129
	v_mov_b32_e32 v65, v129
	v_mov_b32_e32 v66, v129
	v_mov_b32_e32 v67, v129
	v_mov_b32_e32 v68, v129
	v_mov_b32_e32 v69, v129
	v_mov_b32_e32 v70, v129
	v_mov_b32_e32 v71, v129
	v_mov_b32_e32 v72, v129
	v_mov_b32_e32 v73, v129
	v_mov_b32_e32 v74, v129
	v_mov_b32_e32 v75, v129
	v_mov_b32_e32 v76, v129
	v_mov_b32_e32 v77, v129
	v_mov_b32_e32 v78, v129
	v_mov_b32_e32 v79, v129
	v_mov_b64_e32 v[48:49], v[64:65]
	v_mov_b64_e32 v[32:33], v[64:65]
	v_mov_b64_e32 v[16:17], v[64:65]
	v_mov_b32_e32 v220, 0
	v_mov_b32_e32 v221, 0
	v_mov_b32_e32 v223, 0
	v_mov_b32_e32 v222, 0
	v_mov_b32_e32 v210, 0x3f803f80
	v_mov_b32_e32 v211, 0x3f803f80
	v_mov_b64_e32 v[50:51], v[66:67]
	v_mov_b64_e32 v[52:53], v[68:69]
	v_mov_b64_e32 v[54:55], v[70:71]
	v_mov_b64_e32 v[56:57], v[72:73]
	v_mov_b64_e32 v[58:59], v[74:75]
	v_mov_b64_e32 v[60:61], v[76:77]
	v_mov_b64_e32 v[62:63], v[78:79]
	v_mov_b64_e32 v[34:35], v[66:67]
	v_mov_b64_e32 v[36:37], v[68:69]
	v_mov_b64_e32 v[38:39], v[70:71]
	v_mov_b64_e32 v[40:41], v[72:73]
	v_mov_b64_e32 v[42:43], v[74:75]
	v_mov_b64_e32 v[44:45], v[76:77]
	v_mov_b64_e32 v[46:47], v[78:79]
	v_mov_b64_e32 v[18:19], v[66:67]
	v_mov_b64_e32 v[20:21], v[68:69]
	v_mov_b64_e32 v[22:23], v[70:71]
	v_mov_b64_e32 v[24:25], v[72:73]
	v_mov_b64_e32 v[26:27], v[74:75]
	v_mov_b64_e32 v[28:29], v[76:77]
	v_mov_b64_e32 v[30:31], v[78:79]

.LBB0_470:
	s_and_b32 s29, s55, 0x1fc000
	s_cmpk_lt_u32 s57, 0x7f
	s_cselect_b32 s29, s29, 0x1fc000
	s_add_u32 s52, s48, s29
	s_addc_u32 s53, s49, 0
	s_and_b32 s29, s57, 0x7f
	s_mul_i32 s36, s29, 0x230000
	global_load_dwordx4 v[112:115], v201, s[52:53]
	global_load_dwordx4 v[116:119], v208, s[52:53]
	s_add_u32 s52, s50, s36
	s_addc_u32 s53, s51, 0
	global_load_dwordx4 v[120:123], v209, s[52:53]
	global_load_dwordx4 v[124:127], v219, s[52:53]
	s_lshl_b32 s29, s29, 6
	s_sub_i32 s58, s29, s56
	s_add_i32 s36, s58, 0xfffffdb2
	s_cmp_gt_u32 s36, 0xfffffb44
	s_mov_b64 s[52:53], -1
	s_cbranch_scc0 .LBB0_472
	v_sub_u32_e32 v80, s29, v162
	v_lshl_add_u32 v163, v80, 2, v203
	v_add_u32_e32 v163, 0xffc, v163
	ds_read2_b32 v[96:97], v163 offset1:1
	ds_read2_b32 v[80:81], v163 offset0:32 offset1:33
	ds_read2_b32 v[98:99], v163 offset0:2 offset1:3
	ds_read2_b32 v[82:83], v163 offset0:34 offset1:35
	ds_read2_b32 v[100:101], v163 offset0:8 offset1:9
	ds_read2_b32 v[84:85], v163 offset0:40 offset1:41
	ds_read2_b32 v[102:103], v163 offset0:10 offset1:11
	ds_read2_b32 v[86:87], v163 offset0:42 offset1:43
	ds_read2_b32 v[104:105], v163 offset0:16 offset1:17
	ds_read2_b32 v[88:89], v163 offset0:48 offset1:49
	ds_read2_b32 v[106:107], v163 offset0:18 offset1:19
	ds_read2_b32 v[90:91], v163 offset0:50 offset1:51
	ds_read2_b32 v[108:109], v163 offset0:24 offset1:25
	ds_read2_b32 v[92:93], v163 offset0:56 offset1:57
	ds_read2_b32 v[110:111], v163 offset0:26 offset1:27
	ds_read2_b32 v[94:95], v163 offset0:58 offset1:59
	s_mov_b64 s[52:53], 0

.LBB0_474:
	s_add_i32 s52, s57, 1
	s_and_b32 s53, s57, 1
	s_mul_i32 s29, s53, 0x4400
	v_add_u32_e32 v163, s29, v195
	ds_read_b128 v[164:167], v163
	ds_read_b128 v[168:171], v163 offset:32
	ds_read_b128 v[172:175], v163 offset:8704
	ds_read_b128 v[214:217], v163 offset:8736
	s_xor_b32 s29, s53, 1
	s_mulk_i32 s29, 0x5000
	v_add_u32_e32 v176, s29, v202
	s_waitcnt lgkmcnt(3)
	v_mfma_f32_32x32x16_bf16 v[96:111], v[164:167], v[130:133], v[96:111]
	ds_read_b128 v[164:167], v163 offset:64
	ds_read_b64_tr_b16 v[224:225], v176 offset:34816
	ds_read_b64_tr_b16 v[226:227], v176 offset:37376
	v_mfma_f32_4x4x4_16b_bf16 v[220:223], v[210:211], v[158:159], v[220:223]
	s_waitcnt lgkmcnt(4)
	v_mfma_f32_32x32x16_bf16 v[80:95], v[172:175], v[130:133], v[80:95]
	ds_read_b128 v[172:175], v163 offset:8768
	ds_read_b64_tr_b16 v[228:229], v176 offset:34880
	ds_read_b64_tr_b16 v[230:231], v176 offset:37440
	v_mfma_f32_4x4x4_16b_bf16 v[220:223], v[210:211], v[160:161], v[220:223]
	v_mfma_f32_32x32x16_bf16 v[96:111], v[168:171], v[134:137], v[96:111]
	ds_read_b128 v[168:171], v163 offset:96
	ds_read_b64_tr_b16 v[232:233], v176 offset:34944
	ds_read_b64_tr_b16 v[234:235], v176 offset:37504
	v_mfma_f32_4x4x4_16b_bf16 v[220:223], v[210:211], v[154:155], v[220:223]
	s_waitcnt lgkmcnt(9)
	v_mfma_f32_32x32x16_bf16 v[80:95], v[214:217], v[134:137], v[80:95]
	ds_read_b128 v[214:217], v163 offset:8800
	ds_read_b64_tr_b16 v[236:237], v176 offset:35008
	ds_read_b64_tr_b16 v[238:239], v176 offset:37568
	v_mfma_f32_4x4x4_16b_bf16 v[220:223], v[210:211], v[156:157], v[220:223]
	s_nop 1
	v_mfma_f32_4x4x4_16b_bf16 v[220:223], v[210:211], v[150:151], v[220:223]
	s_waitcnt lgkmcnt(11)
	v_mfma_f32_32x32x16_bf16 v[96:111], v[164:167], v[138:141], v[96:111]
	v_mfma_f32_4x4x4_16b_bf16 v[220:223], v[210:211], v[152:153], v[220:223]
	s_waitcnt lgkmcnt(8)
	v_mfma_f32_32x32x16_bf16 v[80:95], v[172:175], v[138:141], v[80:95]
	v_mfma_f32_4x4x4_16b_bf16 v[220:223], v[210:211], v[146:147], v[220:223]
	s_waitcnt lgkmcnt(5)
	v_mfma_f32_32x32x16_bf16 v[96:111], v[168:171], v[142:145], v[96:111]
	v_mfma_f32_4x4x4_16b_bf16 v[220:223], v[210:211], v[148:149], v[220:223]
	s_waitcnt lgkmcnt(2)
	v_mfma_f32_32x32x16_bf16 v[80:95], v[214:217], v[142:145], v[80:95]
	v_mfma_f32_32x32x16_bf16 v[64:79], v[224:227], v[158:161], v[64:79]
	ds_read_b64_tr_b16 v[164:165], v176 offset:39936
	ds_read_b64_tr_b16 v[166:167], v176 offset:42496
	s_nop 4
	v_exp_f32_e32 v163, v96
	v_exp_f32_e32 v172, v97
	v_mfma_f32_32x32x16_bf16 v[48:63], v[228:231], v[158:161], v[48:63]
	ds_read_b64_tr_b16 v[168:169], v176 offset:40000
	ds_read_b64_tr_b16 v[170:171], v176 offset:42560
	v_exp_f32_e32 v173, v98
	v_exp_f32_e32 v174, v99
	v_mfma_f32_32x32x16_bf16 v[32:47], v[232:235], v[158:161], v[32:47]
	ds_read_b64_tr_b16 v[96:97], v176 offset:40064
	ds_read_b64_tr_b16 v[98:99], v176 offset:42624
	v_exp_f32_e32 v175, v100
	v_exp_f32_e32 v177, v101
	s_waitcnt lgkmcnt(6)
	v_mfma_f32_32x32x16_bf16 v[16:31], v[236:239], v[158:161], v[16:31]
	ds_read_b64_tr_b16 v[158:159], v176 offset:40128
	ds_read_b64_tr_b16 v[160:161], v176 offset:42688
	v_exp_f32_e32 v186, v102
	v_exp_f32_e32 v187, v103
	s_waitcnt lgkmcnt(6)
	v_mfma_f32_32x32x16_bf16 v[64:79], v[164:167], v[154:157], v[64:79]
	ds_read_b64_tr_b16 v[100:101], v176 offset:45056
	ds_read_b64_tr_b16 v[102:103], v176 offset:47616
	v_exp_f32_e32 v188, v104
	v_exp_f32_e32 v189, v105
	s_waitcnt lgkmcnt(6)
	v_mfma_f32_32x32x16_bf16 v[48:63], v[168:171], v[154:157], v[48:63]
	ds_read_b64_tr_b16 v[164:165], v176 offset:45120
	ds_read_b64_tr_b16 v[166:167], v176 offset:47680
	v_exp_f32_e32 v168, v106
	v_exp_f32_e32 v169, v107
	s_waitcnt lgkmcnt(6)
	v_mfma_f32_32x32x16_bf16 v[32:47], v[96:99], v[154:157], v[32:47]
	ds_read_b64_tr_b16 v[96:97], v176 offset:45184
	ds_read_b64_tr_b16 v[98:99], v176 offset:47744
	v_exp_f32_e32 v170, v108
	v_exp_f32_e32 v171, v109
	s_waitcnt lgkmcnt(6)
	v_mfma_f32_32x32x16_bf16 v[16:31], v[158:161], v[154:157], v[16:31]
	ds_read_b64_tr_b16 v[104:105], v176 offset:45248
	ds_read_b64_tr_b16 v[106:107], v176 offset:47808
	v_exp_f32_e32 v154, v110
	v_exp_f32_e32 v155, v111
	s_waitcnt lgkmcnt(6)
	v_mfma_f32_32x32x16_bf16 v[64:79], v[100:103], v[150:153], v[64:79]
	ds_read_b64_tr_b16 v[100:101], v176 offset:50176
	ds_read_b64_tr_b16 v[102:103], v176 offset:52736
	v_exp_f32_e32 v156, v80
	v_exp_f32_e32 v157, v81
	s_waitcnt lgkmcnt(6)
	v_mfma_f32_32x32x16_bf16 v[48:63], v[164:167], v[150:153], v[48:63]
	ds_read_b64_tr_b16 v[108:109], v176 offset:50240
	ds_read_b64_tr_b16 v[110:111], v176 offset:52800
	v_exp_f32_e32 v158, v82
	v_exp_f32_e32 v159, v83
	s_waitcnt lgkmcnt(6)
	v_mfma_f32_32x32x16_bf16 v[32:47], v[96:99], v[150:153], v[32:47]
	ds_read_b64_tr_b16 v[80:81], v176 offset:50304
	ds_read_b64_tr_b16 v[82:83], v176 offset:52864
	v_exp_f32_e32 v84, v84
	v_exp_f32_e32 v85, v85
	s_waitcnt lgkmcnt(6)
	v_mfma_f32_32x32x16_bf16 v[16:31], v[104:107], v[150:153], v[16:31]
	ds_read_b64_tr_b16 v[96:97], v176 offset:50368
	ds_read_b64_tr_b16 v[98:99], v176 offset:52928
	v_exp_f32_e32 v86, v86
	v_exp_f32_e32 v87, v87
	s_waitcnt lgkmcnt(6)
	v_mfma_f32_32x32x16_bf16 v[64:79], v[100:103], v[146:149], v[64:79]
	v_exp_f32_e32 v88, v88
	v_exp_f32_e32 v89, v89
	s_waitcnt lgkmcnt(4)
	v_mfma_f32_32x32x16_bf16 v[48:63], v[108:111], v[146:149], v[48:63]
	v_exp_f32_e32 v90, v90
	v_exp_f32_e32 v91, v91
	s_waitcnt lgkmcnt(2)
	v_mfma_f32_32x32x16_bf16 v[32:47], v[80:83], v[146:149], v[32:47]
	v_exp_f32_e32 v80, v92
	v_exp_f32_e32 v81, v93
	s_waitcnt lgkmcnt(0)
	v_mfma_f32_32x32x16_bf16 v[16:31], v[96:99], v[146:149], v[16:31]
	v_cvt_pk_bf16_f32 v148, v80, v81
	v_cvt_pk_bf16_f32 v147, v90, v91
	v_cvt_pk_bf16_f32 v146, v88, v89
	v_cvt_pk_bf16_f32 v153, v86, v87
	v_cvt_pk_bf16_f32 v152, v84, v85
	v_cvt_pk_bf16_f32 v151, v158, v159
	v_cvt_pk_bf16_f32 v150, v156, v157
	v_cvt_pk_bf16_f32 v157, v154, v155
	v_cvt_pk_bf16_f32 v156, v170, v171
	v_cvt_pk_bf16_f32 v155, v168, v169
	v_cvt_pk_bf16_f32 v154, v188, v189
	v_cvt_pk_bf16_f32 v161, v186, v187
	v_cvt_pk_bf16_f32 v160, v175, v177
	v_cvt_pk_bf16_f32 v159, v173, v174
	v_cvt_pk_bf16_f32 v158, v163, v172
	v_exp_f32_e32 v82, v94
	v_exp_f32_e32 v83, v95
	s_bitcmp1_b32 s52, 0
	s_cselect_b32 s29, 0x4400, 0
	s_add_i32 s29, s29, 0
	v_add_u32_e32 v80, s29, v182
	s_mulk_i32 s53, 0x5000
	s_waitcnt vmcnt(3)
	ds_write_b128 v80, v[112:115]
	v_add_u32_e32 v80, s29, v190
	s_add_i32 s29, s53, 0
	s_waitcnt vmcnt(2)
	ds_write_b128 v80, v[116:119]
	v_add_u32_e32 v80, s29, v196
	s_addk_i32 s55, 0x4000
	v_cvt_pk_bf16_f32 v149, v82, v83
	s_waitcnt vmcnt(1)
	ds_write_b128 v80, v[120:123] offset:34816
	v_add_u32_e32 v80, s29, v198
	s_cmp_lt_u32 s52, s54
	s_waitcnt vmcnt(0)
	ds_write_b128 v80, v[124:127] offset:34816
	s_waitcnt lgkmcnt(0)
	s_barrier
	s_cbranch_scc0 .LBB0_477
	s_mov_b32 s57, s52
	s_branch .LBB0_470

.LBB0_479:
	s_add_i32 s55, s54, 1
	s_and_b32 s29, s53, 0x1fc000
	s_cmpk_lg_i32 s54, 0x7f
	s_cselect_b32 s29, s29, 0x1fc000
	s_add_u32 s56, s48, s29
	s_addc_u32 s57, s49, 0
	global_load_dwordx4 v[170:173], v201, s[56:57]
	global_load_dwordx4 v[174:177], v208, s[56:57]
	s_add_u32 s56, s50, s52
	s_addc_u32 s57, s51, 0
	global_load_dwordx4 v[162:165], v209, s[56:57]
	global_load_dwordx4 v[166:169], v219, s[56:57]
	s_and_b32 s56, s54, 1
	s_mul_i32 s29, s56, 0x4400
	v_add_u32_e32 v186, s29, v195
	ds_read_b128 v[96:99], v186
	ds_read_b128 v[214:217], v186 offset:32
	ds_read_b128 v[224:227], v186 offset:8704
	ds_read_b128 v[228:231], v186 offset:8736
	s_xor_b32 s29, s56, 1
	s_mulk_i32 s29, 0x5000
	v_add_u32_e32 v187, s29, v202
	ds_read_b128 v[232:235], v186 offset:64
	ds_read_b64_tr_b16 v[236:237], v187 offset:34816
	ds_read_b64_tr_b16 v[238:239], v187 offset:37376
	v_mfma_f32_4x4x4_16b_bf16 v[220:223], v[210:211], v[158:159], v[220:223]
	s_waitcnt lgkmcnt(6)
	v_mfma_f32_32x32x16_bf16 v[112:127], v[96:99], v[130:133], v[80:95]
	s_waitcnt lgkmcnt(4)
	v_mfma_f32_32x32x16_bf16 v[96:111], v[224:227], v[130:133], v[80:95]
	ds_read_b128 v[224:227], v186 offset:8768
	ds_read_b64_tr_b16 v[240:241], v187 offset:34880
	ds_read_b64_tr_b16 v[242:243], v187 offset:37440
	v_mfma_f32_4x4x4_16b_bf16 v[220:223], v[210:211], v[160:161], v[220:223]
	v_mfma_f32_32x32x16_bf16 v[112:127], v[214:217], v[134:137], v[112:127]
	ds_read_b128 v[214:217], v186 offset:96
	ds_read_b64_tr_b16 v[244:245], v187 offset:34944
	ds_read_b64_tr_b16 v[246:247], v187 offset:37504
	v_mfma_f32_4x4x4_16b_bf16 v[220:223], v[210:211], v[154:155], v[220:223]
	s_waitcnt lgkmcnt(9)
	v_mfma_f32_32x32x16_bf16 v[96:111], v[228:231], v[134:137], v[96:111]
	ds_read_b128 v[228:231], v186 offset:8800
	ds_read_b64_tr_b16 v[248:249], v187 offset:35008
	ds_read_b64_tr_b16 v[250:251], v187 offset:37568
	v_mfma_f32_4x4x4_16b_bf16 v[220:223], v[210:211], v[156:157], v[220:223]
	s_nop 1
	v_mfma_f32_4x4x4_16b_bf16 v[220:223], v[210:211], v[150:151], v[220:223]
	s_waitcnt lgkmcnt(11)
	v_mfma_f32_32x32x16_bf16 v[112:127], v[232:235], v[138:141], v[112:127]
	v_mfma_f32_4x4x4_16b_bf16 v[220:223], v[210:211], v[152:153], v[220:223]
	s_waitcnt lgkmcnt(8)
	v_mfma_f32_32x32x16_bf16 v[96:111], v[224:227], v[138:141], v[96:111]
	v_mfma_f32_4x4x4_16b_bf16 v[220:223], v[210:211], v[146:147], v[220:223]
	s_waitcnt lgkmcnt(5)
	v_mfma_f32_32x32x16_bf16 v[112:127], v[214:217], v[142:145], v[112:127]
	v_mfma_f32_4x4x4_16b_bf16 v[220:223], v[210:211], v[148:149], v[220:223]
	s_waitcnt lgkmcnt(2)
	v_mfma_f32_32x32x16_bf16 v[96:111], v[228:231], v[142:145], v[96:111]
	v_mfma_f32_32x32x16_bf16 v[64:79], v[236:239], v[158:161], v[64:79]
	ds_read_b64_tr_b16 v[214:215], v187 offset:39936
	ds_read_b64_tr_b16 v[216:217], v187 offset:42496
	s_nop 4
	v_exp_f32_e32 v186, v112
	v_exp_f32_e32 v188, v113
	v_mfma_f32_32x32x16_bf16 v[48:63], v[240:243], v[158:161], v[48:63]
	ds_read_b64_tr_b16 v[224:225], v187 offset:40000
	ds_read_b64_tr_b16 v[226:227], v187 offset:42560
	v_exp_f32_e32 v189, v114
	v_exp_f32_e32 v212, v115
	v_mfma_f32_32x32x16_bf16 v[32:47], v[244:247], v[158:161], v[32:47]
	ds_read_b64_tr_b16 v[112:113], v187 offset:40064
	ds_read_b64_tr_b16 v[114:115], v187 offset:42624
	v_exp_f32_e32 v213, v116
	v_exp_f32_e32 v228, v117
	s_waitcnt lgkmcnt(6)
	v_mfma_f32_32x32x16_bf16 v[16:31], v[248:251], v[158:161], v[16:31]
	ds_read_b64_tr_b16 v[158:159], v187 offset:40128
	ds_read_b64_tr_b16 v[160:161], v187 offset:42688
	v_exp_f32_e32 v229, v118
	v_exp_f32_e32 v230, v119
	s_waitcnt lgkmcnt(6)
	v_mfma_f32_32x32x16_bf16 v[64:79], v[214:217], v[154:157], v[64:79]
	ds_read_b64_tr_b16 v[116:117], v187 offset:45056
	ds_read_b64_tr_b16 v[118:119], v187 offset:47616
	v_exp_f32_e32 v231, v120
	v_exp_f32_e32 v232, v121
	s_waitcnt lgkmcnt(6)
	v_mfma_f32_32x32x16_bf16 v[48:63], v[224:227], v[154:157], v[48:63]
	ds_read_b64_tr_b16 v[214:215], v187 offset:45120
	ds_read_b64_tr_b16 v[216:217], v187 offset:47680
	v_exp_f32_e32 v224, v122
	v_exp_f32_e32 v225, v123
	s_waitcnt lgkmcnt(6)
	v_mfma_f32_32x32x16_bf16 v[32:47], v[112:115], v[154:157], v[32:47]
	ds_read_b64_tr_b16 v[112:113], v187 offset:45184
	ds_read_b64_tr_b16 v[114:115], v187 offset:47744
	v_exp_f32_e32 v226, v124
	v_exp_f32_e32 v227, v125
	s_waitcnt lgkmcnt(6)
	v_mfma_f32_32x32x16_bf16 v[16:31], v[158:161], v[154:157], v[16:31]
	ds_read_b64_tr_b16 v[120:121], v187 offset:45248
	ds_read_b64_tr_b16 v[122:123], v187 offset:47808
	v_exp_f32_e32 v154, v126
	v_exp_f32_e32 v155, v127
	s_waitcnt lgkmcnt(6)
	v_mfma_f32_32x32x16_bf16 v[64:79], v[116:119], v[150:153], v[64:79]
	ds_read_b64_tr_b16 v[116:117], v187 offset:50176
	ds_read_b64_tr_b16 v[118:119], v187 offset:52736
	v_exp_f32_e32 v156, v96
	v_exp_f32_e32 v157, v97
	s_waitcnt lgkmcnt(6)
	v_mfma_f32_32x32x16_bf16 v[48:63], v[214:217], v[150:153], v[48:63]
	ds_read_b64_tr_b16 v[124:125], v187 offset:50240
	ds_read_b64_tr_b16 v[126:127], v187 offset:52800
	v_exp_f32_e32 v158, v98
	v_exp_f32_e32 v159, v99
	s_waitcnt lgkmcnt(6)
	v_mfma_f32_32x32x16_bf16 v[32:47], v[112:115], v[150:153], v[32:47]
	ds_read_b64_tr_b16 v[96:97], v187 offset:50304
	ds_read_b64_tr_b16 v[98:99], v187 offset:52864
	v_exp_f32_e32 v100, v100
	v_exp_f32_e32 v101, v101
	s_waitcnt lgkmcnt(6)
	v_mfma_f32_32x32x16_bf16 v[16:31], v[120:123], v[150:153], v[16:31]
	ds_read_b64_tr_b16 v[112:113], v187 offset:50368
	ds_read_b64_tr_b16 v[114:115], v187 offset:52928
	s_bitcmp1_b32 s55, 0
	s_cselect_b32 s29, 0x4400, 0
	s_add_i32 s29, s29, 0
	v_add_u32_e32 v187, s29, v182
	s_mulk_i32 s56, 0x5000
	s_waitcnt vmcnt(3)
	ds_write_b128 v187, v[170:173]
	v_add_u32_e32 v187, s29, v190
	s_add_i32 s29, s56, 0
	s_waitcnt vmcnt(2)
; DI float shx(float v, int m, int lane) { return __int_as_float(__builtin_amdgcn_ds_bpermute((lane ^ m) << 2, __float_as_int(v))); }
; template <int KW, int DQK, int DV, int MODE> ...
;     ...
;     rowsum_pw(pw, ls);
;     pv_tile<DV, VP>(o, pw, lds + ((NT - 1) & 1) * VT + voff);
;     l = (ls[0] + ls[1]) + (ls[2] + ls[3]);
;     __syncthreads();
;     ...
;     l += shx(l, 32, lane);
	ds_write_b128 v187, v[174:177]
	v_add_u32_e32 v187, s29, v196
	s_waitcnt vmcnt(1)
	ds_write_b128 v187, v[162:165] offset:34816
	v_add_u32_e32 v187, s29, v198
	s_waitcnt vmcnt(0)
	ds_write_b128 v187, v[166:169] offset:34816
	v_exp_f32_e32 v102, v102
	v_exp_f32_e32 v103, v103
	s_waitcnt lgkmcnt(10)
	v_mfma_f32_32x32x16_bf16 v[64:79], v[116:119], v[146:149], v[64:79]
	v_exp_f32_e32 v104, v104
	v_exp_f32_e32 v105, v105
	s_waitcnt lgkmcnt(8)
	v_mfma_f32_32x32x16_bf16 v[48:63], v[124:127], v[146:149], v[48:63]
	v_exp_f32_e32 v106, v106
	v_exp_f32_e32 v107, v107
	s_waitcnt lgkmcnt(6)
	v_mfma_f32_32x32x16_bf16 v[32:47], v[96:99], v[146:149], v[32:47]
	v_exp_f32_e32 v96, v108
	v_exp_f32_e32 v97, v109
	s_waitcnt lgkmcnt(4)
	v_mfma_f32_32x32x16_bf16 v[16:31], v[112:115], v[146:149], v[16:31]
	v_cvt_pk_bf16_f32 v148, v96, v97
	v_cvt_pk_bf16_f32 v147, v106, v107
	v_cvt_pk_bf16_f32 v146, v104, v105
	v_cvt_pk_bf16_f32 v153, v102, v103
	v_cvt_pk_bf16_f32 v152, v100, v101
	v_cvt_pk_bf16_f32 v151, v158, v159
	v_cvt_pk_bf16_f32 v150, v156, v157
	v_cvt_pk_bf16_f32 v157, v154, v155
	v_cvt_pk_bf16_f32 v156, v226, v227
	v_cvt_pk_bf16_f32 v155, v224, v225
	v_cvt_pk_bf16_f32 v154, v231, v232
	v_cvt_pk_bf16_f32 v161, v229, v230
	v_cvt_pk_bf16_f32 v160, v213, v228
	v_cvt_pk_bf16_f32 v159, v189, v212
	v_cvt_pk_bf16_f32 v158, v186, v188
	v_exp_f32_e32 v98, v110
	v_exp_f32_e32 v99, v111
	s_add_i32 s52, s52, 0x230000
	s_addk_i32 s53, 0x4000
	v_cvt_pk_bf16_f32 v149, v98, v99
	s_cmpk_lt_u32 s54, 0x7f
	s_mov_b32 s54, s55
	s_waitcnt lgkmcnt(0)
	s_barrier
	s_cbranch_scc1 .LBB0_479
.LBB0_480:
	ds_read_b64_tr_b16 v[82:83], v202 offset:57856
	ds_read_b64_tr_b16 v[80:81], v202 offset:55296
	ds_read_b64_tr_b16 v[84:85], v202 offset:55360
	v_mfma_f32_4x4x4_16b_bf16 v[220:223], v[210:211], v[158:159], v[220:223]
	s_nop 1
	v_mfma_f32_4x4x4_16b_bf16 v[220:223], v[210:211], v[160:161], v[220:223]
	s_waitcnt lgkmcnt(1)
	v_mfma_f32_32x32x16_bf16 v[64:79], v[80:83], v[158:161], v[64:79]
	ds_read_b64_tr_b16 v[86:87], v202 offset:57920
	ds_read_b64_tr_b16 v[80:81], v202 offset:55424
	v_mfma_f32_4x4x4_16b_bf16 v[220:223], v[210:211], v[154:155], v[220:223]
	s_nop 1
	v_mfma_f32_4x4x4_16b_bf16 v[220:223], v[210:211], v[156:157], v[220:223]
	s_nop 1
	v_mfma_f32_4x4x4_16b_bf16 v[220:223], v[210:211], v[150:151], v[220:223]
	s_waitcnt lgkmcnt(1)
	v_mfma_f32_32x32x16_bf16 v[48:63], v[84:87], v[158:161], v[48:63]
	ds_read_b64_tr_b16 v[82:83], v202 offset:57984
	ds_read_b64_tr_b16 v[84:85], v202 offset:55488
	v_mfma_f32_4x4x4_16b_bf16 v[220:223], v[210:211], v[152:153], v[220:223]
	s_nop 1
	v_mfma_f32_4x4x4_16b_bf16 v[220:223], v[210:211], v[146:147], v[220:223]
	s_nop 1
	v_mfma_f32_4x4x4_16b_bf16 v[220:223], v[210:211], v[148:149], v[220:223]
	s_waitcnt lgkmcnt(1)
	v_mfma_f32_32x32x16_bf16 v[32:47], v[80:83], v[158:161], v[32:47]
	ds_read_b64_tr_b16 v[86:87], v202 offset:58048
	ds_read_b64_tr_b16 v[82:83], v202 offset:62976
	s_waitcnt lgkmcnt(1)
	v_mfma_f32_32x32x16_bf16 v[16:31], v[84:87], v[158:161], v[16:31]
	ds_read_b64_tr_b16 v[80:81], v202 offset:60416
	ds_read_b64_tr_b16 v[84:85], v202 offset:60480
	s_waitcnt lgkmcnt(1)
	v_mfma_f32_32x32x16_bf16 v[64:79], v[80:83], v[154:157], v[64:79]
	ds_read_b64_tr_b16 v[86:87], v202 offset:63040
	ds_read_b64_tr_b16 v[80:81], v202 offset:60544
	s_waitcnt lgkmcnt(1)
	v_mfma_f32_32x32x16_bf16 v[48:63], v[84:87], v[154:157], v[48:63]
	ds_read_b64_tr_b16 v[82:83], v202 offset:63104
	ds_read_b64_tr_b16 v[84:85], v202 offset:60608
	s_waitcnt lgkmcnt(1)
	v_mfma_f32_32x32x16_bf16 v[32:47], v[80:83], v[154:157], v[32:47]
	ds_read_b64_tr_b16 v[86:87], v202 offset:63168
	ds_read_b64_tr_b16 v[80:81], v204 offset:10240
	ds_read_b64_tr_b16 v[82:83], v204 offset:12800
	s_waitcnt lgkmcnt(2)
	v_mfma_f32_32x32x16_bf16 v[16:31], v[84:87], v[154:157], v[16:31]
	ds_read_b64_tr_b16 v[84:85], v204 offset:10304
	ds_read_b64_tr_b16 v[88:89], v204 offset:10368
	ds_read_b64_tr_b16 v[92:93], v204 offset:10432
	ds_read_b64_tr_b16 v[86:87], v204 offset:12864
	ds_read_b64_tr_b16 v[90:91], v204 offset:12928
	ds_read_b64_tr_b16 v[94:95], v204 offset:12992
	s_waitcnt lgkmcnt(6)
	v_mfma_f32_32x32x16_bf16 v[64:79], v[80:83], v[150:153], v[64:79]
	ds_read_b64_tr_b16 v[80:81], v204 offset:15360
	ds_read_b64_tr_b16 v[82:83], v204 offset:17920
	s_waitcnt lgkmcnt(4)
	v_mfma_f32_32x32x16_bf16 v[48:63], v[84:87], v[150:153], v[48:63]
	v_mov_b32_e32 v98, v220
	ds_bpermute_b32 v99, v205, v98
	s_waitcnt lgkmcnt(4)
	v_mfma_f32_32x32x16_bf16 v[32:47], v[88:91], v[150:153], v[32:47]
	s_waitcnt lgkmcnt(3)
	v_mfma_f32_32x32x16_bf16 v[16:31], v[92:95], v[150:153], v[16:31]
	s_waitcnt lgkmcnt(0)
	v_add_f32_e32 v92, v98, v99
	ds_read_b64_tr_b16 v[84:85], v204 offset:15424
	ds_read_b64_tr_b16 v[88:89], v204 offset:15488
	ds_read_b64_tr_b16 v[94:95], v204 offset:15552
	ds_read_b64_tr_b16 v[86:87], v204 offset:17984
	ds_read_b64_tr_b16 v[90:91], v204 offset:18048
	ds_read_b64_tr_b16 v[96:97], v204 offset:18112
	s_waitcnt lgkmcnt(0)
	s_barrier
; #define RELANE(x) int x = (int)__builtin_amdgcn_mbcnt_hi(~0u, __builtin_amdgcn_mbcnt_lo(~0u, 0u)); asm volatile("" : "+v"(x));
; __global__ void __launch_bounds__(512) mega(Params P) {
;     ...
;                     const float linv = 1.0f / lsum;
;                     RELANE(l2) int u2 = u; asm volatile("" : "+s"(u2));
;                     const int h2 = u2 >> 6, q02 = (u2 & 63) * 128 + (wid & 3) * 32, hi2 = l2 >> 5;
;                     if (map == 1) {
; #pragma unroll
;                         for (int d0 = 0; d0 < 4; ++d0)
; #pragma unroll
;                             for (int r = 0; r < 16; ++r) xch[(d0 * 16 + r) * 256 + (wid & 3) * 64 + l2] = o[d0][r] * linv;
;                     }
	v_mfma_f32_32x32x16_bf16 v[64:79], v[80:83], v[146:149], v[64:79]
	v_div_scale_f32 v80, s[48:49], v92, v92, 1.0
	v_rcp_f32_e32 v81, v80
	s_mov_b32 s48, s78
	v_fma_f32 v82, -v80, v81, 1.0
	v_mfma_f32_32x32x16_bf16 v[48:63], v[84:87], v[146:149], v[48:63]
	v_fmac_f32_e32 v81, v82, v81
	v_div_scale_f32 v82, vcc, 1.0, v92, 1.0
	v_mul_f32_e32 v83, v82, v81
	v_fma_f32 v84, -v80, v83, v82
	v_fmac_f32_e32 v83, v84, v81
	v_fma_f32 v80, -v80, v83, v82
	v_mfma_f32_32x32x16_bf16 v[32:47], v[88:91], v[146:149], v[32:47]
	v_div_fmas_f32 v80, v80, v81, v83
	v_div_fixup_f32 v92, v80, v92, 1.0
	v_mov_b32_e32 v80, v252
	s_andn2_b64 vcc, exec, s[20:21]
	v_mfma_f32_32x32x16_bf16 v[16:31], v[94:97], v[146:149], v[16:31]
	s_cbranch_vccnz .LBB0_482
	v_lshl_add_u32 v81, v80, 2, s85
	v_mul_f32_e32 v82, v92, v64
	v_mul_f32_e32 v83, v92, v65
	ds_write2st64_b32 v81, v82, v83 offset1:4
	v_mul_f32_e32 v82, v92, v66
	v_mul_f32_e32 v83, v92, v67
	ds_write2st64_b32 v81, v82, v83 offset0:8 offset1:12
	v_mul_f32_e32 v82, v92, v68
	v_mul_f32_e32 v83, v92, v69
	ds_write2st64_b32 v81, v82, v83 offset0:16 offset1:20
	v_mul_f32_e32 v82, v92, v70
	v_mul_f32_e32 v83, v92, v71
	ds_write2st64_b32 v81, v82, v83 offset0:24 offset1:28
	v_mul_f32_e32 v82, v92, v72
	v_mul_f32_e32 v83, v92, v73
	ds_write2st64_b32 v81, v82, v83 offset0:32 offset1:36
	v_mul_f32_e32 v82, v92, v74
	v_mul_f32_e32 v83, v92, v75
	ds_write2st64_b32 v81, v82, v83 offset0:40 offset1:44
	v_mul_f32_e32 v82, v92, v76
	v_mul_f32_e32 v83, v92, v77
	ds_write2st64_b32 v81, v82, v83 offset0:48 offset1:52
	v_mul_f32_e32 v82, v92, v78
	v_mul_f32_e32 v83, v92, v79
	ds_write2st64_b32 v81, v82, v83 offset0:56 offset1:60
	v_mul_f32_e32 v82, v92, v48
	v_mul_f32_e32 v83, v92, v49
	ds_write2st64_b32 v81, v82, v83 offset0:64 offset1:68
	v_mul_f32_e32 v82, v92, v50
	v_mul_f32_e32 v83, v92, v51
	ds_write2st64_b32 v81, v82, v83 offset0:72 offset1:76
	v_mul_f32_e32 v82, v92, v52
	v_mul_f32_e32 v83, v92, v53
	ds_write2st64_b32 v81, v82, v83 offset0:80 offset1:84
	v_mul_f32_e32 v82, v92, v54
	v_mul_f32_e32 v83, v92, v55
	ds_write2st64_b32 v81, v82, v83 offset0:88 offset1:92
	v_mul_f32_e32 v82, v92, v56
	v_mul_f32_e32 v83, v92, v57
	ds_write2st64_b32 v81, v82, v83 offset0:96 offset1:100
	v_mul_f32_e32 v82, v92, v58
	v_mul_f32_e32 v83, v92, v59
	ds_write2st64_b32 v81, v82, v83 offset0:104 offset1:108
	v_mul_f32_e32 v82, v92, v60
	v_mul_f32_e32 v83, v92, v61
	ds_write2st64_b32 v81, v82, v83 offset0:112 offset1:116
	v_mul_f32_e32 v82, v92, v62
	v_mul_f32_e32 v83, v92, v63
	ds_write2st64_b32 v81, v82, v83 offset0:120 offset1:124
	v_mul_f32_e32 v82, v92, v32
	v_mul_f32_e32 v83, v92, v33
	ds_write2st64_b32 v81, v82, v83 offset0:128 offset1:132
	v_mul_f32_e32 v82, v92, v34
	v_mul_f32_e32 v83, v92, v35
	ds_write2st64_b32 v81, v82, v83 offset0:136 offset1:140
	v_mul_f32_e32 v82, v92, v36
	v_mul_f32_e32 v83, v92, v37
	ds_write2st64_b32 v81, v82, v83 offset0:144 offset1:148
	v_mul_f32_e32 v82, v92, v38
	v_mul_f32_e32 v83, v92, v39
	ds_write2st64_b32 v81, v82, v83 offset0:152 offset1:156
	v_mul_f32_e32 v82, v92, v40
	v_mul_f32_e32 v83, v92, v41
	ds_write2st64_b32 v81, v82, v83 offset0:160 offset1:164
	v_mul_f32_e32 v82, v92, v42
	v_mul_f32_e32 v83, v92, v43
	ds_write2st64_b32 v81, v82, v83 offset0:168 offset1:172
	v_mul_f32_e32 v82, v92, v44
	v_mul_f32_e32 v83, v92, v45
	ds_write2st64_b32 v81, v82, v83 offset0:176 offset1:180
	v_mul_f32_e32 v82, v92, v46
	v_mul_f32_e32 v83, v92, v47
	ds_write2st64_b32 v81, v82, v83 offset0:184 offset1:188
	v_mul_f32_e32 v82, v92, v16
	v_mul_f32_e32 v83, v92, v17
	ds_write2st64_b32 v81, v82, v83 offset0:192 offset1:196
	v_mul_f32_e32 v82, v92, v18
	v_mul_f32_e32 v83, v92, v19
	ds_write2st64_b32 v81, v82, v83 offset0:200 offset1:204
	v_mul_f32_e32 v82, v92, v20
	v_mul_f32_e32 v83, v92, v21
	ds_write2st64_b32 v81, v82, v83 offset0:208 offset1:212
	v_mul_f32_e32 v82, v92, v22
	v_mul_f32_e32 v83, v92, v23
	ds_write2st64_b32 v81, v82, v83 offset0:216 offset1:220
	v_mul_f32_e32 v82, v92, v24
	v_mul_f32_e32 v83, v92, v25
	ds_write2st64_b32 v81, v82, v83 offset0:224 offset1:228
	v_mul_f32_e32 v82, v92, v26
	v_mul_f32_e32 v83, v92, v27
	ds_write2st64_b32 v81, v82, v83 offset0:232 offset1:236
	v_mul_f32_e32 v82, v92, v28
	v_mul_f32_e32 v83, v92, v29
	ds_write2st64_b32 v81, v82, v83 offset0:240 offset1:244
	v_mul_f32_e32 v82, v92, v30
	v_mul_f32_e32 v83, v92, v31
	ds_write2st64_b32 v81, v82, v83 offset0:248 offset1:252

; #define LAS __attribute__((address_space(3)))
; DI float shx(float v, int m, int lane) { return __int_as_float(__builtin_amdgcn_ds_bpermute((lane ^ m) << 2, __float_as_int(v))); }
; DI float uni(float v) { return __int_as_float(__builtin_amdgcn_readfirstlane(__float_as_int(v))); }
; #define RELANE(x) int x = (int)__builtin_amdgcn_mbcnt_hi(~0u, __builtin_amdgcn_mbcnt_lo(~0u, 0u)); asm volatile("" : "+v"(x));
; __global__ void __launch_bounds__(512) mega(Params P) {
;     ...
;             for (int rc_ = 0; rc_ < ((REP_MASK >> 11) & 1) + 1; ++rc_)
;             {
;                 PHASE_BEGIN const int r32 = lane & 31, hi = lane >> 5;
;                 float nbound;
;                 { RELANE(l6)
;                   float maxb = 0.f;
;                   for (int i = l6; i < 32 * 28; i += 64) maxb = fmaxf(maxb, fabsf(P.rel_bias[i]));
; #pragma unroll
;                   for (int o_ = 1; o_ < 64; o_ <<= 1) maxb = fmaxf(maxb, shx(maxb, o_, l6));
;                   float wmax = 0.f;
;                   for (int g_ = 0; g_ < 3; ++g_) wmax = fmaxf(wmax, wave_absmax(P.dil_qk_norm + ((l * 2 + 0) * 3 + g_) * 64, 64, l6) * wave_absmax(P.dil_qk_norm + ((l * 2 + 1) * 3 + g_) * 64, 64, l6));
;                   nbound = uni(-((64.0f * 0.125f * LOG2E * 1.02f) * wmax + maxb * LOG2E)); }
;                 constexpr int CKP = 144, CVP = 144, CKT = 64 * CKP, CWB = CKT + 64 * CVP;
;                 constexpr int CR0 = 576, CR1 = 192, CR2 = 128, CT1 = 2 * CR0 + 1, CT2 = CT1 + 2 * CR1 + 1, CTN = CT2 + 2 * CR2 + 1;
;                 LAS float* ctab = (LAS float*)(lds + 8 * CWB);
;                 LAS unsigned char* wl = lds + wid * CWB;
;                 for (int u = vcu; u < 256; u += G) {
.LBB0_484:
	v_mov_b32_e32 v219, 0x1fff
	v_mov_b32_e32 v220, 0xff800000
	v_readlane_b32 s0, v253, 56
	v_readlane_b32 s86, v253, 16
	v_readlane_b32 s1, v253, 57
	s_mov_b32 s20, s86
	v_mov_b32_e32 v0, v252
	v_readlane_b32 s21, v253, 17
	s_and_b64 vcc, exec, s[0:1]
	s_cbranch_vccz .LBB0_486
	s_ashr_i32 s0, s21, 31
	s_lshr_b32 s0, s0, 29
	s_add_i32 s0, s21, s0
	s_ashr_i32 s1, s0, 3
	s_and_b32 s0, s0, -8
	s_sub_i32 s0, s21, s0
	v_readlane_b32 s2, v253, 58
	s_mul_i32 s0, s0, s2
	s_add_i32 s21, s0, s1
